# final RMSNorm row loop through a 4-buffer ring with three rows of loads in flight
# baseline (speedup 1.0000x reference)
; __device__ __forceinline__ void final_norm(float* x, const float* gam, int tid) {
;   const int lane = tid & 63; const int gw = blockIdx.x * 8 + (tid >> 6), nw = gridDim.x * 8;
;   for (int r = gw; r < SEQ; r += nw) {
;     f32x4* xr = (f32x4*)(x + (size_t)r * DM) + lane;
;     f32x4 v[8]; float ss = 0.f;
; #pragma unroll
;     for (int j = 0; j < 8; ++j) { v[j] = xr[64 * j]; ss += v[j][0] * v[j][0] + v[j][1] * v[j][1] + v[j][2] * v[j][2] + v[j][3] * v[j][3]; }
;     const float rstd = rsqrtf(wave_sum(ss) * (1.0f / DM) + 1e-6f);
.LBB0_459:
	s_andn2_b64 vcc, exec, s[2:3]
	s_cbranch_vccnz .LBB0_464
	v_ashrrev_i32_e32 v0, 6, v146
	v_readlane_b32 s2, v253, 19
	s_nop 1
	v_add_u32_e32 v0, s2, v0
	s_movk_i32 s2, 0x4000
	v_cmp_gt_i32_e32 vcc, s2, v0
	s_and_saveexec_b64 s[2:3], vcc
	v_readlane_b32 s8, v253, 51
	v_readlane_b32 s9, v253, 52
	s_cbranch_execz .LBB0_463
	v_readlane_b32 s10, v254, 9
	v_readlane_b32 s11, v254, 10
	s_load_dwordx4 s[4:7], s[10:11], 0x100
	v_lshlrev_b32_e32 v1, 4, v229
	v_and_b32_e32 v138, 0x3f0, v1
	v_ashrrev_i32_e32 v1, 31, v0
	v_lshlrev_b64 v[12:13], 13, v[0:1]
	s_waitcnt lgkmcnt(0)
	v_lshl_add_u64 v[2:3], s[4:5], 0, v[138:139]
	s_mov_b64 s[4:5], 0x1400
	v_lshl_add_u64 v[6:7], v[2:3], 0, s[4:5]
	s_mov_b64 s[4:5], 0x1800
	v_or_b32_e32 v12, v12, v138
	s_mov_b64 s[10:11], 0x1000
	v_lshl_add_u64 v[8:9], v[2:3], 0, s[4:5]
	s_mov_b64 s[4:5], 0x1c00
	v_lshl_add_u64 v[12:13], s[6:7], 0, v[12:13]
	v_lshl_add_u64 v[4:5], v[2:3], 0, s[10:11]
	v_lshl_add_u64 v[10:11], v[2:3], 0, s[4:5]
	v_lshl_add_u64 v[12:13], v[12:13], 0, s[10:11]
	s_mov_b64 s[4:5], 0
	global_load_dwordx4 v[180:183], v[2:3], off
	global_load_dwordx4 v[184:187], v[2:3], off offset:1024
	global_load_dwordx4 v[188:191], v[2:3], off offset:2048
	global_load_dwordx4 v[192:195], v[2:3], off offset:3072
	global_load_dwordx4 v[196:199], v[4:5], off
	global_load_dwordx4 v[200:203], v[6:7], off
	global_load_dwordx4 v[204:207], v[8:9], off
	global_load_dwordx4 v[208:211], v[10:11], off
	v_mbcnt_lo_u32_b32 v232, -1, 0
	v_mbcnt_hi_u32_b32 v232, -1, v232
	v_lshlrev_b32_e32 v232, 2, v232
	v_xor_b32_e32 v222, 4, v232
	v_xor_b32_e32 v223, 8, v232
	v_xor_b32_e32 v224, 16, v232
	v_xor_b32_e32 v225, 32, v232
	v_xor_b32_e32 v230, 64, v232
	v_xor_b32_e32 v231, 0x80, v232
	v_mov_b32_e32 v244, v12
	v_mov_b32_e32 v245, v13
	v_mov_b32_e32 v246, v12
	v_mov_b32_e32 v247, v13
	v_readfirstlane_b32 s4, v0
	s_mov_b32 s5, s4
	s_cmp_lt_i32 s5, 0x4000
	s_cselect_b64 vcc, -1, 0
	v_cndmask_b32_e32 v234, v246, v244, vcc
	v_cndmask_b32_e32 v235, v247, v245, vcc
	global_load_dwordx4 v[16:19], v[234:235], off offset:-4096
	global_load_dwordx4 v[20:23], v[234:235], off offset:-3072
	global_load_dwordx4 v[24:27], v[234:235], off offset:-2048
	global_load_dwordx4 v[28:31], v[234:235], off offset:-1024
	global_load_dwordx4 v[32:35], v[234:235], off
	global_load_dwordx4 v[36:39], v[234:235], off offset:1024
	global_load_dwordx4 v[40:43], v[234:235], off offset:2048
	global_load_dwordx4 v[44:47], v[234:235], off offset:3072
	v_lshl_add_u64 v[244:245], v[244:245], 0, s[8:9]
	s_add_i32 s5, s5, s82
	s_cmp_lt_i32 s5, 0x4000
	s_cselect_b64 vcc, -1, 0
	v_cndmask_b32_e32 v236, v246, v244, vcc
	v_cndmask_b32_e32 v237, v247, v245, vcc
	global_load_dwordx4 v[48:51], v[236:237], off offset:-4096
	global_load_dwordx4 v[52:55], v[236:237], off offset:-3072
	global_load_dwordx4 v[56:59], v[236:237], off offset:-2048
	global_load_dwordx4 v[60:63], v[236:237], off offset:-1024
	global_load_dwordx4 v[64:67], v[236:237], off
	global_load_dwordx4 v[68:71], v[236:237], off offset:1024
	global_load_dwordx4 v[72:75], v[236:237], off offset:2048
	global_load_dwordx4 v[76:79], v[236:237], off offset:3072
	v_lshl_add_u64 v[244:245], v[244:245], 0, s[8:9]
	s_add_i32 s5, s5, s82
	s_cmp_lt_i32 s5, 0x4000
	s_cselect_b64 vcc, -1, 0
	v_cndmask_b32_e32 v238, v246, v244, vcc
	v_cndmask_b32_e32 v239, v247, v245, vcc
	global_load_dwordx4 v[80:83], v[238:239], off offset:-4096
	global_load_dwordx4 v[84:87], v[238:239], off offset:-3072
	global_load_dwordx4 v[88:91], v[238:239], off offset:-2048
	global_load_dwordx4 v[92:95], v[238:239], off offset:-1024
	global_load_dwordx4 v[96:99], v[238:239], off
	global_load_dwordx4 v[100:103], v[238:239], off offset:1024
	global_load_dwordx4 v[104:107], v[238:239], off offset:2048
	global_load_dwordx4 v[108:111], v[238:239], off offset:3072
	v_lshl_add_u64 v[244:245], v[244:245], 0, s[8:9]
	s_add_i32 s5, s5, s82
	s_cmp_lt_i32 s5, 0x4000
	s_cselect_b64 vcc, -1, 0
	v_cndmask_b32_e32 v240, v246, v244, vcc
	v_cndmask_b32_e32 v241, v247, v245, vcc
	global_load_dwordx4 v[148:151], v[240:241], off offset:-4096
	global_load_dwordx4 v[152:155], v[240:241], off offset:-3072
	global_load_dwordx4 v[156:159], v[240:241], off offset:-2048
	global_load_dwordx4 v[160:163], v[240:241], off offset:-1024
	global_load_dwordx4 v[164:167], v[240:241], off
	global_load_dwordx4 v[168:171], v[240:241], off offset:1024
	global_load_dwordx4 v[172:175], v[240:241], off offset:2048
	global_load_dwordx4 v[176:179], v[240:241], off offset:3072
	v_lshl_add_u64 v[244:245], v[244:245], 0, s[8:9]
	s_add_i32 s5, s5, s82
	s_waitcnt vmcnt(24)
	v_pk_mul_f32 v[212:213], v[16:17], v[16:17]
	v_pk_fma_f32 v[212:213], v[18:19], v[18:19], v[212:213]
	v_pk_mul_f32 v[214:215], v[20:21], v[20:21]
	v_pk_fma_f32 v[214:215], v[22:23], v[22:23], v[214:215]
	v_pk_mul_f32 v[216:217], v[24:25], v[24:25]
	v_pk_fma_f32 v[216:217], v[26:27], v[26:27], v[216:217]
	v_pk_mul_f32 v[218:219], v[28:29], v[28:29]
	v_pk_fma_f32 v[218:219], v[30:31], v[30:31], v[218:219]
	v_pk_fma_f32 v[212:213], v[32:33], v[32:33], v[212:213]
	v_pk_fma_f32 v[212:213], v[34:35], v[34:35], v[212:213]
	v_pk_fma_f32 v[214:215], v[36:37], v[36:37], v[214:215]
	v_pk_fma_f32 v[214:215], v[38:39], v[38:39], v[214:215]
	v_pk_fma_f32 v[216:217], v[40:41], v[40:41], v[216:217]
	v_pk_fma_f32 v[216:217], v[42:43], v[42:43], v[216:217]
	v_pk_fma_f32 v[218:219], v[44:45], v[44:45], v[218:219]
	v_pk_fma_f32 v[218:219], v[46:47], v[46:47], v[218:219]
	v_pk_add_f32 v[212:213], v[212:213], v[214:215]
	v_pk_add_f32 v[216:217], v[216:217], v[218:219]
	v_pk_add_f32 v[212:213], v[212:213], v[216:217]
	v_add_f32_e32 v220, v212, v213
	ds_bpermute_b32 v221, v222, v220
	s_waitcnt lgkmcnt(0)
; __device__ __forceinline__ void final_norm(float* x, const float* gam, int tid) {
;     ...
;     for (int j = 0; j < 8; ++j) { v[j] = xr[64 * j]; ss += v[j][0] * v[j][0] + v[j][1] * v[j][1] + v[j][2] * v[j][2] + v[j][3] * v[j][3]; }
;     const float rstd = rsqrtf(wave_sum(ss) * (1.0f / DM) + 1e-6f);
; #pragma unroll
;     for (int j = 0; j < 8; ++j) xr[64 * j] = v[j] * rstd * *(const f32x4*)(gam + 4 * (lane + 64 * j));
	v_add_f32_e32 v220, v220, v221
	ds_bpermute_b32 v221, v223, v220
	s_waitcnt lgkmcnt(0)
	v_add_f32_e32 v220, v220, v221
	ds_bpermute_b32 v221, v224, v220
	s_waitcnt lgkmcnt(0)
	v_add_f32_e32 v220, v220, v221
	ds_bpermute_b32 v221, v225, v220
	s_waitcnt lgkmcnt(0)
	v_add_f32_e32 v220, v220, v221
	ds_bpermute_b32 v221, v230, v220
	s_waitcnt lgkmcnt(0)
	v_add_f32_e32 v220, v220, v221
	ds_bpermute_b32 v221, v231, v220
	s_waitcnt lgkmcnt(0)
	v_add_f32_e32 v220, v220, v221
	v_fmamk_f32 v220, v220, 0x3a000000, v228
	v_mul_f32_e32 v221, 0x4b800000, v220
	v_cmp_gt_f32_e32 vcc, s67, v220
	s_nop 1
	v_cndmask_b32_e32 v220, v220, v221, vcc
	v_rsq_f32_e32 v220, v220
	s_nop 0
	v_mul_f32_e32 v221, 0x45800000, v220
	v_cndmask_b32_e32 v220, v220, v221, vcc
	v_pk_mul_f32 v[16:17], v[16:17], v[220:221] op_sel_hi:[1,0]
	v_pk_mul_f32 v[16:17], v[180:181], v[16:17]
	v_pk_mul_f32 v[18:19], v[18:19], v[220:221] op_sel_hi:[1,0]
	v_pk_mul_f32 v[18:19], v[182:183], v[18:19]
	global_store_dwordx4 v[234:235], v[16:19], off offset:-4096
	v_pk_mul_f32 v[20:21], v[20:21], v[220:221] op_sel_hi:[1,0]
	v_pk_mul_f32 v[20:21], v[184:185], v[20:21]
	v_pk_mul_f32 v[22:23], v[22:23], v[220:221] op_sel_hi:[1,0]
	v_pk_mul_f32 v[22:23], v[186:187], v[22:23]
	global_store_dwordx4 v[234:235], v[20:23], off offset:-3072
	v_pk_mul_f32 v[24:25], v[24:25], v[220:221] op_sel_hi:[1,0]
	v_pk_mul_f32 v[24:25], v[188:189], v[24:25]
	v_pk_mul_f32 v[26:27], v[26:27], v[220:221] op_sel_hi:[1,0]
	v_pk_mul_f32 v[26:27], v[190:191], v[26:27]
	global_store_dwordx4 v[234:235], v[24:27], off offset:-2048
	v_pk_mul_f32 v[28:29], v[28:29], v[220:221] op_sel_hi:[1,0]
	v_pk_mul_f32 v[28:29], v[192:193], v[28:29]
	v_pk_mul_f32 v[30:31], v[30:31], v[220:221] op_sel_hi:[1,0]
	v_pk_mul_f32 v[30:31], v[194:195], v[30:31]
	global_store_dwordx4 v[234:235], v[28:31], off offset:-1024
	v_pk_mul_f32 v[32:33], v[32:33], v[220:221] op_sel_hi:[1,0]
	v_pk_mul_f32 v[32:33], v[196:197], v[32:33]
	v_pk_mul_f32 v[34:35], v[34:35], v[220:221] op_sel_hi:[1,0]
	v_pk_mul_f32 v[34:35], v[198:199], v[34:35]
	global_store_dwordx4 v[234:235], v[32:35], off
	v_pk_mul_f32 v[36:37], v[36:37], v[220:221] op_sel_hi:[1,0]
	v_pk_mul_f32 v[36:37], v[200:201], v[36:37]
	v_pk_mul_f32 v[38:39], v[38:39], v[220:221] op_sel_hi:[1,0]
	v_pk_mul_f32 v[38:39], v[202:203], v[38:39]
	global_store_dwordx4 v[234:235], v[36:39], off offset:1024
	v_pk_mul_f32 v[40:41], v[40:41], v[220:221] op_sel_hi:[1,0]
	v_pk_mul_f32 v[40:41], v[204:205], v[40:41]
	v_pk_mul_f32 v[42:43], v[42:43], v[220:221] op_sel_hi:[1,0]
	v_pk_mul_f32 v[42:43], v[206:207], v[42:43]
	global_store_dwordx4 v[234:235], v[40:43], off offset:2048
	v_pk_mul_f32 v[44:45], v[44:45], v[220:221] op_sel_hi:[1,0]
	v_pk_mul_f32 v[44:45], v[208:209], v[44:45]
	v_pk_mul_f32 v[46:47], v[46:47], v[220:221] op_sel_hi:[1,0]
	v_pk_mul_f32 v[46:47], v[210:211], v[46:47]
	global_store_dwordx4 v[234:235], v[44:47], off offset:3072
	s_add_i32 s4, s4, s82
	s_cmp_lt_i32 s4, 0x4000
	s_cbranch_scc0 .Lfn_done
	s_cmp_lt_i32 s5, 0x4000
	s_cselect_b64 vcc, -1, 0
	v_cndmask_b32_e32 v234, v246, v244, vcc
	v_cndmask_b32_e32 v235, v247, v245, vcc
	global_load_dwordx4 v[16:19], v[234:235], off offset:-4096
	global_load_dwordx4 v[20:23], v[234:235], off offset:-3072
	global_load_dwordx4 v[24:27], v[234:235], off offset:-2048
	global_load_dwordx4 v[28:31], v[234:235], off offset:-1024
	global_load_dwordx4 v[32:35], v[234:235], off
	global_load_dwordx4 v[36:39], v[234:235], off offset:1024
	global_load_dwordx4 v[40:43], v[234:235], off offset:2048
	global_load_dwordx4 v[44:47], v[234:235], off offset:3072
	v_lshl_add_u64 v[244:245], v[244:245], 0, s[8:9]
	s_add_i32 s5, s5, s82
	s_waitcnt vmcnt(32)
	v_pk_mul_f32 v[212:213], v[48:49], v[48:49]
	v_pk_fma_f32 v[212:213], v[50:51], v[50:51], v[212:213]
	v_pk_mul_f32 v[214:215], v[52:53], v[52:53]
	v_pk_fma_f32 v[214:215], v[54:55], v[54:55], v[214:215]
	v_pk_mul_f32 v[216:217], v[56:57], v[56:57]
	v_pk_fma_f32 v[216:217], v[58:59], v[58:59], v[216:217]
	v_pk_mul_f32 v[218:219], v[60:61], v[60:61]
	v_pk_fma_f32 v[218:219], v[62:63], v[62:63], v[218:219]
	v_pk_fma_f32 v[212:213], v[64:65], v[64:65], v[212:213]
	v_pk_fma_f32 v[212:213], v[66:67], v[66:67], v[212:213]
	v_pk_fma_f32 v[214:215], v[68:69], v[68:69], v[214:215]
	v_pk_fma_f32 v[214:215], v[70:71], v[70:71], v[214:215]
	v_pk_fma_f32 v[216:217], v[72:73], v[72:73], v[216:217]
	v_pk_fma_f32 v[216:217], v[74:75], v[74:75], v[216:217]
	v_pk_fma_f32 v[218:219], v[76:77], v[76:77], v[218:219]
	v_pk_fma_f32 v[218:219], v[78:79], v[78:79], v[218:219]
	v_pk_add_f32 v[212:213], v[212:213], v[214:215]
	v_pk_add_f32 v[216:217], v[216:217], v[218:219]
	v_pk_add_f32 v[212:213], v[212:213], v[216:217]
	v_add_f32_e32 v220, v212, v213
	ds_bpermute_b32 v221, v222, v220
	s_waitcnt lgkmcnt(0)
	v_add_f32_e32 v220, v220, v221
	ds_bpermute_b32 v221, v223, v220
	s_waitcnt lgkmcnt(0)
	v_add_f32_e32 v220, v220, v221
	ds_bpermute_b32 v221, v224, v220
	s_waitcnt lgkmcnt(0)
	v_add_f32_e32 v220, v220, v221
	ds_bpermute_b32 v221, v225, v220
	s_waitcnt lgkmcnt(0)
	v_add_f32_e32 v220, v220, v221
	ds_bpermute_b32 v221, v230, v220
	s_waitcnt lgkmcnt(0)
	v_add_f32_e32 v220, v220, v221
	ds_bpermute_b32 v221, v231, v220
	s_waitcnt lgkmcnt(0)
; __device__ __forceinline__ void final_norm(float* x, const float* gam, int tid) {
;     ...
;     for (int j = 0; j < 8; ++j) { v[j] = xr[64 * j]; ss += v[j][0] * v[j][0] + v[j][1] * v[j][1] + v[j][2] * v[j][2] + v[j][3] * v[j][3]; }
;     const float rstd = rsqrtf(wave_sum(ss) * (1.0f / DM) + 1e-6f);
; #pragma unroll
;     for (int j = 0; j < 8; ++j) xr[64 * j] = v[j] * rstd * *(const f32x4*)(gam + 4 * (lane + 64 * j));
	v_add_f32_e32 v220, v220, v221
	v_fmamk_f32 v220, v220, 0x3a000000, v228
	v_mul_f32_e32 v221, 0x4b800000, v220
	v_cmp_gt_f32_e32 vcc, s67, v220
	s_nop 1
	v_cndmask_b32_e32 v220, v220, v221, vcc
	v_rsq_f32_e32 v220, v220
	s_nop 0
	v_mul_f32_e32 v221, 0x45800000, v220
	v_cndmask_b32_e32 v220, v220, v221, vcc
	v_pk_mul_f32 v[48:49], v[48:49], v[220:221] op_sel_hi:[1,0]
	v_pk_mul_f32 v[48:49], v[180:181], v[48:49]
	v_pk_mul_f32 v[50:51], v[50:51], v[220:221] op_sel_hi:[1,0]
	v_pk_mul_f32 v[50:51], v[182:183], v[50:51]
	global_store_dwordx4 v[236:237], v[48:51], off offset:-4096
	v_pk_mul_f32 v[52:53], v[52:53], v[220:221] op_sel_hi:[1,0]
	v_pk_mul_f32 v[52:53], v[184:185], v[52:53]
	v_pk_mul_f32 v[54:55], v[54:55], v[220:221] op_sel_hi:[1,0]
	v_pk_mul_f32 v[54:55], v[186:187], v[54:55]
	global_store_dwordx4 v[236:237], v[52:55], off offset:-3072
	v_pk_mul_f32 v[56:57], v[56:57], v[220:221] op_sel_hi:[1,0]
	v_pk_mul_f32 v[56:57], v[188:189], v[56:57]
	v_pk_mul_f32 v[58:59], v[58:59], v[220:221] op_sel_hi:[1,0]
	v_pk_mul_f32 v[58:59], v[190:191], v[58:59]
	global_store_dwordx4 v[236:237], v[56:59], off offset:-2048
	v_pk_mul_f32 v[60:61], v[60:61], v[220:221] op_sel_hi:[1,0]
	v_pk_mul_f32 v[60:61], v[192:193], v[60:61]
	v_pk_mul_f32 v[62:63], v[62:63], v[220:221] op_sel_hi:[1,0]
	v_pk_mul_f32 v[62:63], v[194:195], v[62:63]
	global_store_dwordx4 v[236:237], v[60:63], off offset:-1024
	v_pk_mul_f32 v[64:65], v[64:65], v[220:221] op_sel_hi:[1,0]
	v_pk_mul_f32 v[64:65], v[196:197], v[64:65]
	v_pk_mul_f32 v[66:67], v[66:67], v[220:221] op_sel_hi:[1,0]
	v_pk_mul_f32 v[66:67], v[198:199], v[66:67]
	global_store_dwordx4 v[236:237], v[64:67], off
	v_pk_mul_f32 v[68:69], v[68:69], v[220:221] op_sel_hi:[1,0]
	v_pk_mul_f32 v[68:69], v[200:201], v[68:69]
	v_pk_mul_f32 v[70:71], v[70:71], v[220:221] op_sel_hi:[1,0]
	v_pk_mul_f32 v[70:71], v[202:203], v[70:71]
	global_store_dwordx4 v[236:237], v[68:71], off offset:1024
	v_pk_mul_f32 v[72:73], v[72:73], v[220:221] op_sel_hi:[1,0]
	v_pk_mul_f32 v[72:73], v[204:205], v[72:73]
	v_pk_mul_f32 v[74:75], v[74:75], v[220:221] op_sel_hi:[1,0]
	v_pk_mul_f32 v[74:75], v[206:207], v[74:75]
	global_store_dwordx4 v[236:237], v[72:75], off offset:2048
	v_pk_mul_f32 v[76:77], v[76:77], v[220:221] op_sel_hi:[1,0]
	v_pk_mul_f32 v[76:77], v[208:209], v[76:77]
	v_pk_mul_f32 v[78:79], v[78:79], v[220:221] op_sel_hi:[1,0]
	v_pk_mul_f32 v[78:79], v[210:211], v[78:79]
	global_store_dwordx4 v[236:237], v[76:79], off offset:3072
	s_add_i32 s4, s4, s82
	s_cmp_lt_i32 s4, 0x4000
	s_cbranch_scc0 .Lfn_done
	s_cmp_lt_i32 s5, 0x4000
	s_cselect_b64 vcc, -1, 0
	v_cndmask_b32_e32 v236, v246, v244, vcc
	v_cndmask_b32_e32 v237, v247, v245, vcc
	global_load_dwordx4 v[48:51], v[236:237], off offset:-4096
	global_load_dwordx4 v[52:55], v[236:237], off offset:-3072
	global_load_dwordx4 v[56:59], v[236:237], off offset:-2048
	global_load_dwordx4 v[60:63], v[236:237], off offset:-1024
	global_load_dwordx4 v[64:67], v[236:237], off
	global_load_dwordx4 v[68:71], v[236:237], off offset:1024
	global_load_dwordx4 v[72:75], v[236:237], off offset:2048
	global_load_dwordx4 v[76:79], v[236:237], off offset:3072
	v_lshl_add_u64 v[244:245], v[244:245], 0, s[8:9]
	s_add_i32 s5, s5, s82
	s_waitcnt vmcnt(40)
	v_pk_mul_f32 v[212:213], v[80:81], v[80:81]
	v_pk_fma_f32 v[212:213], v[82:83], v[82:83], v[212:213]
	v_pk_mul_f32 v[214:215], v[84:85], v[84:85]
	v_pk_fma_f32 v[214:215], v[86:87], v[86:87], v[214:215]
	v_pk_mul_f32 v[216:217], v[88:89], v[88:89]
	v_pk_fma_f32 v[216:217], v[90:91], v[90:91], v[216:217]
	v_pk_mul_f32 v[218:219], v[92:93], v[92:93]
	v_pk_fma_f32 v[218:219], v[94:95], v[94:95], v[218:219]
	v_pk_fma_f32 v[212:213], v[96:97], v[96:97], v[212:213]
	v_pk_fma_f32 v[212:213], v[98:99], v[98:99], v[212:213]
	v_pk_fma_f32 v[214:215], v[100:101], v[100:101], v[214:215]
	v_pk_fma_f32 v[214:215], v[102:103], v[102:103], v[214:215]
	v_pk_fma_f32 v[216:217], v[104:105], v[104:105], v[216:217]
	v_pk_fma_f32 v[216:217], v[106:107], v[106:107], v[216:217]
	v_pk_fma_f32 v[218:219], v[108:109], v[108:109], v[218:219]
	v_pk_fma_f32 v[218:219], v[110:111], v[110:111], v[218:219]
	v_pk_add_f32 v[212:213], v[212:213], v[214:215]
	v_pk_add_f32 v[216:217], v[216:217], v[218:219]
	v_pk_add_f32 v[212:213], v[212:213], v[216:217]
	v_add_f32_e32 v220, v212, v213
	ds_bpermute_b32 v221, v222, v220
	s_waitcnt lgkmcnt(0)
	v_add_f32_e32 v220, v220, v221
	ds_bpermute_b32 v221, v223, v220
	s_waitcnt lgkmcnt(0)
	v_add_f32_e32 v220, v220, v221
	ds_bpermute_b32 v221, v224, v220
	s_waitcnt lgkmcnt(0)
	v_add_f32_e32 v220, v220, v221
	ds_bpermute_b32 v221, v225, v220
	s_waitcnt lgkmcnt(0)
	v_add_f32_e32 v220, v220, v221
	ds_bpermute_b32 v221, v230, v220
	s_waitcnt lgkmcnt(0)
	v_add_f32_e32 v220, v220, v221
	ds_bpermute_b32 v221, v231, v220
	s_waitcnt lgkmcnt(0)
; __device__ __forceinline__ void final_norm(float* x, const float* gam, int tid) {
;     ...
;     for (int j = 0; j < 8; ++j) { v[j] = xr[64 * j]; ss += v[j][0] * v[j][0] + v[j][1] * v[j][1] + v[j][2] * v[j][2] + v[j][3] * v[j][3]; }
;     const float rstd = rsqrtf(wave_sum(ss) * (1.0f / DM) + 1e-6f);
; #pragma unroll
;     for (int j = 0; j < 8; ++j) xr[64 * j] = v[j] * rstd * *(const f32x4*)(gam + 4 * (lane + 64 * j));
	v_add_f32_e32 v220, v220, v221
	v_fmamk_f32 v220, v220, 0x3a000000, v228
	v_mul_f32_e32 v221, 0x4b800000, v220
	v_cmp_gt_f32_e32 vcc, s67, v220
	s_nop 1
	v_cndmask_b32_e32 v220, v220, v221, vcc
	v_rsq_f32_e32 v220, v220
	s_nop 0
	v_mul_f32_e32 v221, 0x45800000, v220
	v_cndmask_b32_e32 v220, v220, v221, vcc
	v_pk_mul_f32 v[80:81], v[80:81], v[220:221] op_sel_hi:[1,0]
	v_pk_mul_f32 v[80:81], v[180:181], v[80:81]
	v_pk_mul_f32 v[82:83], v[82:83], v[220:221] op_sel_hi:[1,0]
	v_pk_mul_f32 v[82:83], v[182:183], v[82:83]
	global_store_dwordx4 v[238:239], v[80:83], off offset:-4096
	v_pk_mul_f32 v[84:85], v[84:85], v[220:221] op_sel_hi:[1,0]
	v_pk_mul_f32 v[84:85], v[184:185], v[84:85]
	v_pk_mul_f32 v[86:87], v[86:87], v[220:221] op_sel_hi:[1,0]
	v_pk_mul_f32 v[86:87], v[186:187], v[86:87]
	global_store_dwordx4 v[238:239], v[84:87], off offset:-3072
	v_pk_mul_f32 v[88:89], v[88:89], v[220:221] op_sel_hi:[1,0]
	v_pk_mul_f32 v[88:89], v[188:189], v[88:89]
	v_pk_mul_f32 v[90:91], v[90:91], v[220:221] op_sel_hi:[1,0]
	v_pk_mul_f32 v[90:91], v[190:191], v[90:91]
	global_store_dwordx4 v[238:239], v[88:91], off offset:-2048
	v_pk_mul_f32 v[92:93], v[92:93], v[220:221] op_sel_hi:[1,0]
	v_pk_mul_f32 v[92:93], v[192:193], v[92:93]
	v_pk_mul_f32 v[94:95], v[94:95], v[220:221] op_sel_hi:[1,0]
	v_pk_mul_f32 v[94:95], v[194:195], v[94:95]
	global_store_dwordx4 v[238:239], v[92:95], off offset:-1024
	v_pk_mul_f32 v[96:97], v[96:97], v[220:221] op_sel_hi:[1,0]
	v_pk_mul_f32 v[96:97], v[196:197], v[96:97]
	v_pk_mul_f32 v[98:99], v[98:99], v[220:221] op_sel_hi:[1,0]
	v_pk_mul_f32 v[98:99], v[198:199], v[98:99]
	global_store_dwordx4 v[238:239], v[96:99], off
	v_pk_mul_f32 v[100:101], v[100:101], v[220:221] op_sel_hi:[1,0]
	v_pk_mul_f32 v[100:101], v[200:201], v[100:101]
	v_pk_mul_f32 v[102:103], v[102:103], v[220:221] op_sel_hi:[1,0]
	v_pk_mul_f32 v[102:103], v[202:203], v[102:103]
	global_store_dwordx4 v[238:239], v[100:103], off offset:1024
	v_pk_mul_f32 v[104:105], v[104:105], v[220:221] op_sel_hi:[1,0]
	v_pk_mul_f32 v[104:105], v[204:205], v[104:105]
	v_pk_mul_f32 v[106:107], v[106:107], v[220:221] op_sel_hi:[1,0]
	v_pk_mul_f32 v[106:107], v[206:207], v[106:107]
	global_store_dwordx4 v[238:239], v[104:107], off offset:2048
	v_pk_mul_f32 v[108:109], v[108:109], v[220:221] op_sel_hi:[1,0]
	v_pk_mul_f32 v[108:109], v[208:209], v[108:109]
	v_pk_mul_f32 v[110:111], v[110:111], v[220:221] op_sel_hi:[1,0]
	v_pk_mul_f32 v[110:111], v[210:211], v[110:111]
	global_store_dwordx4 v[238:239], v[108:111], off offset:3072
	s_add_i32 s4, s4, s82
	s_cmp_lt_i32 s4, 0x4000
	s_cbranch_scc0 .Lfn_done
.Lfn_loop:
	s_cmp_lt_i32 s5, 0x4000
	s_cselect_b64 vcc, -1, 0
	v_cndmask_b32_e32 v238, v246, v244, vcc
	v_cndmask_b32_e32 v239, v247, v245, vcc
	global_load_dwordx4 v[80:83], v[238:239], off offset:-4096
	global_load_dwordx4 v[84:87], v[238:239], off offset:-3072
	global_load_dwordx4 v[88:91], v[238:239], off offset:-2048
	global_load_dwordx4 v[92:95], v[238:239], off offset:-1024
	global_load_dwordx4 v[96:99], v[238:239], off
	global_load_dwordx4 v[100:103], v[238:239], off offset:1024
	global_load_dwordx4 v[104:107], v[238:239], off offset:2048
	global_load_dwordx4 v[108:111], v[238:239], off offset:3072
	v_lshl_add_u64 v[244:245], v[244:245], 0, s[8:9]
	s_add_i32 s5, s5, s82
	s_waitcnt vmcnt(48)
	v_pk_mul_f32 v[212:213], v[148:149], v[148:149]
	v_pk_fma_f32 v[212:213], v[150:151], v[150:151], v[212:213]
	v_pk_mul_f32 v[214:215], v[152:153], v[152:153]
	v_pk_fma_f32 v[214:215], v[154:155], v[154:155], v[214:215]
	v_pk_mul_f32 v[216:217], v[156:157], v[156:157]
	v_pk_fma_f32 v[216:217], v[158:159], v[158:159], v[216:217]
	v_pk_mul_f32 v[218:219], v[160:161], v[160:161]
	v_pk_fma_f32 v[218:219], v[162:163], v[162:163], v[218:219]
	v_pk_fma_f32 v[212:213], v[164:165], v[164:165], v[212:213]
	v_pk_fma_f32 v[212:213], v[166:167], v[166:167], v[212:213]
	v_pk_fma_f32 v[214:215], v[168:169], v[168:169], v[214:215]
	v_pk_fma_f32 v[214:215], v[170:171], v[170:171], v[214:215]
	v_pk_fma_f32 v[216:217], v[172:173], v[172:173], v[216:217]
	v_pk_fma_f32 v[216:217], v[174:175], v[174:175], v[216:217]
	v_pk_fma_f32 v[218:219], v[176:177], v[176:177], v[218:219]
	v_pk_fma_f32 v[218:219], v[178:179], v[178:179], v[218:219]
	v_pk_add_f32 v[212:213], v[212:213], v[214:215]
	v_pk_add_f32 v[216:217], v[216:217], v[218:219]
	v_pk_add_f32 v[212:213], v[212:213], v[216:217]
	v_add_f32_e32 v220, v212, v213
	ds_bpermute_b32 v221, v222, v220
	s_waitcnt lgkmcnt(0)
	v_add_f32_e32 v220, v220, v221
	ds_bpermute_b32 v221, v223, v220
	s_waitcnt lgkmcnt(0)
	v_add_f32_e32 v220, v220, v221
	ds_bpermute_b32 v221, v224, v220
	s_waitcnt lgkmcnt(0)
	v_add_f32_e32 v220, v220, v221
	ds_bpermute_b32 v221, v225, v220
	s_waitcnt lgkmcnt(0)
	v_add_f32_e32 v220, v220, v221
	ds_bpermute_b32 v221, v230, v220
	s_waitcnt lgkmcnt(0)
	v_add_f32_e32 v220, v220, v221
	ds_bpermute_b32 v221, v231, v220
	s_waitcnt lgkmcnt(0)
; __device__ __forceinline__ void final_norm(float* x, const float* gam, int tid) {
;     ...
;     for (int j = 0; j < 8; ++j) { v[j] = xr[64 * j]; ss += v[j][0] * v[j][0] + v[j][1] * v[j][1] + v[j][2] * v[j][2] + v[j][3] * v[j][3]; }
;     const float rstd = rsqrtf(wave_sum(ss) * (1.0f / DM) + 1e-6f);
; #pragma unroll
;     for (int j = 0; j < 8; ++j) xr[64 * j] = v[j] * rstd * *(const f32x4*)(gam + 4 * (lane + 64 * j));
	v_add_f32_e32 v220, v220, v221
	v_fmamk_f32 v220, v220, 0x3a000000, v228
	v_mul_f32_e32 v221, 0x4b800000, v220
	v_cmp_gt_f32_e32 vcc, s67, v220
	s_nop 1
	v_cndmask_b32_e32 v220, v220, v221, vcc
	v_rsq_f32_e32 v220, v220
	s_nop 0
	v_mul_f32_e32 v221, 0x45800000, v220
	v_cndmask_b32_e32 v220, v220, v221, vcc
	v_pk_mul_f32 v[148:149], v[148:149], v[220:221] op_sel_hi:[1,0]
	v_pk_mul_f32 v[148:149], v[180:181], v[148:149]
	v_pk_mul_f32 v[150:151], v[150:151], v[220:221] op_sel_hi:[1,0]
	v_pk_mul_f32 v[150:151], v[182:183], v[150:151]
	global_store_dwordx4 v[240:241], v[148:151], off offset:-4096
	v_pk_mul_f32 v[152:153], v[152:153], v[220:221] op_sel_hi:[1,0]
	v_pk_mul_f32 v[152:153], v[184:185], v[152:153]
	v_pk_mul_f32 v[154:155], v[154:155], v[220:221] op_sel_hi:[1,0]
	v_pk_mul_f32 v[154:155], v[186:187], v[154:155]
	global_store_dwordx4 v[240:241], v[152:155], off offset:-3072
	v_pk_mul_f32 v[156:157], v[156:157], v[220:221] op_sel_hi:[1,0]
	v_pk_mul_f32 v[156:157], v[188:189], v[156:157]
	v_pk_mul_f32 v[158:159], v[158:159], v[220:221] op_sel_hi:[1,0]
	v_pk_mul_f32 v[158:159], v[190:191], v[158:159]
	global_store_dwordx4 v[240:241], v[156:159], off offset:-2048
	v_pk_mul_f32 v[160:161], v[160:161], v[220:221] op_sel_hi:[1,0]
	v_pk_mul_f32 v[160:161], v[192:193], v[160:161]
	v_pk_mul_f32 v[162:163], v[162:163], v[220:221] op_sel_hi:[1,0]
	v_pk_mul_f32 v[162:163], v[194:195], v[162:163]
	global_store_dwordx4 v[240:241], v[160:163], off offset:-1024
	v_pk_mul_f32 v[164:165], v[164:165], v[220:221] op_sel_hi:[1,0]
	v_pk_mul_f32 v[164:165], v[196:197], v[164:165]
	v_pk_mul_f32 v[166:167], v[166:167], v[220:221] op_sel_hi:[1,0]
	v_pk_mul_f32 v[166:167], v[198:199], v[166:167]
	global_store_dwordx4 v[240:241], v[164:167], off
	v_pk_mul_f32 v[168:169], v[168:169], v[220:221] op_sel_hi:[1,0]
	v_pk_mul_f32 v[168:169], v[200:201], v[168:169]
	v_pk_mul_f32 v[170:171], v[170:171], v[220:221] op_sel_hi:[1,0]
	v_pk_mul_f32 v[170:171], v[202:203], v[170:171]
	global_store_dwordx4 v[240:241], v[168:171], off offset:1024
	v_pk_mul_f32 v[172:173], v[172:173], v[220:221] op_sel_hi:[1,0]
	v_pk_mul_f32 v[172:173], v[204:205], v[172:173]
	v_pk_mul_f32 v[174:175], v[174:175], v[220:221] op_sel_hi:[1,0]
	v_pk_mul_f32 v[174:175], v[206:207], v[174:175]
	global_store_dwordx4 v[240:241], v[172:175], off offset:2048
	v_pk_mul_f32 v[176:177], v[176:177], v[220:221] op_sel_hi:[1,0]
	v_pk_mul_f32 v[176:177], v[208:209], v[176:177]
	v_pk_mul_f32 v[178:179], v[178:179], v[220:221] op_sel_hi:[1,0]
	v_pk_mul_f32 v[178:179], v[210:211], v[178:179]
	global_store_dwordx4 v[240:241], v[176:179], off offset:3072
	s_add_i32 s4, s4, s82
	s_cmp_lt_i32 s4, 0x4000
	s_cbranch_scc0 .Lfn_done
	s_cmp_lt_i32 s5, 0x4000
	s_cselect_b64 vcc, -1, 0
	v_cndmask_b32_e32 v240, v246, v244, vcc
	v_cndmask_b32_e32 v241, v247, v245, vcc
	global_load_dwordx4 v[148:151], v[240:241], off offset:-4096
	global_load_dwordx4 v[152:155], v[240:241], off offset:-3072
	global_load_dwordx4 v[156:159], v[240:241], off offset:-2048
	global_load_dwordx4 v[160:163], v[240:241], off offset:-1024
	global_load_dwordx4 v[164:167], v[240:241], off
	global_load_dwordx4 v[168:171], v[240:241], off offset:1024
	global_load_dwordx4 v[172:175], v[240:241], off offset:2048
	global_load_dwordx4 v[176:179], v[240:241], off offset:3072
	v_lshl_add_u64 v[244:245], v[244:245], 0, s[8:9]
	s_add_i32 s5, s5, s82
	s_waitcnt vmcnt(48)
	v_pk_mul_f32 v[212:213], v[16:17], v[16:17]
	v_pk_fma_f32 v[212:213], v[18:19], v[18:19], v[212:213]
	v_pk_mul_f32 v[214:215], v[20:21], v[20:21]
	v_pk_fma_f32 v[214:215], v[22:23], v[22:23], v[214:215]
	v_pk_mul_f32 v[216:217], v[24:25], v[24:25]
	v_pk_fma_f32 v[216:217], v[26:27], v[26:27], v[216:217]
	v_pk_mul_f32 v[218:219], v[28:29], v[28:29]
	v_pk_fma_f32 v[218:219], v[30:31], v[30:31], v[218:219]
	v_pk_fma_f32 v[212:213], v[32:33], v[32:33], v[212:213]
	v_pk_fma_f32 v[212:213], v[34:35], v[34:35], v[212:213]
	v_pk_fma_f32 v[214:215], v[36:37], v[36:37], v[214:215]
	v_pk_fma_f32 v[214:215], v[38:39], v[38:39], v[214:215]
	v_pk_fma_f32 v[216:217], v[40:41], v[40:41], v[216:217]
	v_pk_fma_f32 v[216:217], v[42:43], v[42:43], v[216:217]
	v_pk_fma_f32 v[218:219], v[44:45], v[44:45], v[218:219]
	v_pk_fma_f32 v[218:219], v[46:47], v[46:47], v[218:219]
	v_pk_add_f32 v[212:213], v[212:213], v[214:215]
	v_pk_add_f32 v[216:217], v[216:217], v[218:219]
	v_pk_add_f32 v[212:213], v[212:213], v[216:217]
	v_add_f32_e32 v220, v212, v213
	ds_bpermute_b32 v221, v222, v220
	s_waitcnt lgkmcnt(0)
	v_add_f32_e32 v220, v220, v221
	ds_bpermute_b32 v221, v223, v220
	s_waitcnt lgkmcnt(0)
	v_add_f32_e32 v220, v220, v221
	ds_bpermute_b32 v221, v224, v220
	s_waitcnt lgkmcnt(0)
	v_add_f32_e32 v220, v220, v221
	ds_bpermute_b32 v221, v225, v220
	s_waitcnt lgkmcnt(0)
	v_add_f32_e32 v220, v220, v221
	ds_bpermute_b32 v221, v230, v220
	s_waitcnt lgkmcnt(0)
	v_add_f32_e32 v220, v220, v221
	ds_bpermute_b32 v221, v231, v220
	s_waitcnt lgkmcnt(0)
; __device__ __forceinline__ void final_norm(float* x, const float* gam, int tid) {
;     ...
;     for (int j = 0; j < 8; ++j) { v[j] = xr[64 * j]; ss += v[j][0] * v[j][0] + v[j][1] * v[j][1] + v[j][2] * v[j][2] + v[j][3] * v[j][3]; }
;     const float rstd = rsqrtf(wave_sum(ss) * (1.0f / DM) + 1e-6f);
; #pragma unroll
;     for (int j = 0; j < 8; ++j) xr[64 * j] = v[j] * rstd * *(const f32x4*)(gam + 4 * (lane + 64 * j));
	v_add_f32_e32 v220, v220, v221
	v_fmamk_f32 v220, v220, 0x3a000000, v228
	v_mul_f32_e32 v221, 0x4b800000, v220
	v_cmp_gt_f32_e32 vcc, s67, v220
	s_nop 1
	v_cndmask_b32_e32 v220, v220, v221, vcc
	v_rsq_f32_e32 v220, v220
	s_nop 0
	v_mul_f32_e32 v221, 0x45800000, v220
	v_cndmask_b32_e32 v220, v220, v221, vcc
	v_pk_mul_f32 v[16:17], v[16:17], v[220:221] op_sel_hi:[1,0]
	v_pk_mul_f32 v[16:17], v[180:181], v[16:17]
	v_pk_mul_f32 v[18:19], v[18:19], v[220:221] op_sel_hi:[1,0]
	v_pk_mul_f32 v[18:19], v[182:183], v[18:19]
	global_store_dwordx4 v[234:235], v[16:19], off offset:-4096
	v_pk_mul_f32 v[20:21], v[20:21], v[220:221] op_sel_hi:[1,0]
	v_pk_mul_f32 v[20:21], v[184:185], v[20:21]
	v_pk_mul_f32 v[22:23], v[22:23], v[220:221] op_sel_hi:[1,0]
	v_pk_mul_f32 v[22:23], v[186:187], v[22:23]
	global_store_dwordx4 v[234:235], v[20:23], off offset:-3072
	v_pk_mul_f32 v[24:25], v[24:25], v[220:221] op_sel_hi:[1,0]
	v_pk_mul_f32 v[24:25], v[188:189], v[24:25]
	v_pk_mul_f32 v[26:27], v[26:27], v[220:221] op_sel_hi:[1,0]
	v_pk_mul_f32 v[26:27], v[190:191], v[26:27]
	global_store_dwordx4 v[234:235], v[24:27], off offset:-2048
	v_pk_mul_f32 v[28:29], v[28:29], v[220:221] op_sel_hi:[1,0]
	v_pk_mul_f32 v[28:29], v[192:193], v[28:29]
	v_pk_mul_f32 v[30:31], v[30:31], v[220:221] op_sel_hi:[1,0]
	v_pk_mul_f32 v[30:31], v[194:195], v[30:31]
	global_store_dwordx4 v[234:235], v[28:31], off offset:-1024
	v_pk_mul_f32 v[32:33], v[32:33], v[220:221] op_sel_hi:[1,0]
	v_pk_mul_f32 v[32:33], v[196:197], v[32:33]
	v_pk_mul_f32 v[34:35], v[34:35], v[220:221] op_sel_hi:[1,0]
	v_pk_mul_f32 v[34:35], v[198:199], v[34:35]
	global_store_dwordx4 v[234:235], v[32:35], off
	v_pk_mul_f32 v[36:37], v[36:37], v[220:221] op_sel_hi:[1,0]
	v_pk_mul_f32 v[36:37], v[200:201], v[36:37]
	v_pk_mul_f32 v[38:39], v[38:39], v[220:221] op_sel_hi:[1,0]
	v_pk_mul_f32 v[38:39], v[202:203], v[38:39]
	global_store_dwordx4 v[234:235], v[36:39], off offset:1024
	v_pk_mul_f32 v[40:41], v[40:41], v[220:221] op_sel_hi:[1,0]
	v_pk_mul_f32 v[40:41], v[204:205], v[40:41]
	v_pk_mul_f32 v[42:43], v[42:43], v[220:221] op_sel_hi:[1,0]
	v_pk_mul_f32 v[42:43], v[206:207], v[42:43]
	global_store_dwordx4 v[234:235], v[40:43], off offset:2048
	v_pk_mul_f32 v[44:45], v[44:45], v[220:221] op_sel_hi:[1,0]
	v_pk_mul_f32 v[44:45], v[208:209], v[44:45]
	v_pk_mul_f32 v[46:47], v[46:47], v[220:221] op_sel_hi:[1,0]
	v_pk_mul_f32 v[46:47], v[210:211], v[46:47]
	global_store_dwordx4 v[234:235], v[44:47], off offset:3072
	s_add_i32 s4, s4, s82
	s_cmp_lt_i32 s4, 0x4000
	s_cbranch_scc0 .Lfn_done
	s_cmp_lt_i32 s5, 0x4000
	s_cselect_b64 vcc, -1, 0
	v_cndmask_b32_e32 v234, v246, v244, vcc
	v_cndmask_b32_e32 v235, v247, v245, vcc
	global_load_dwordx4 v[16:19], v[234:235], off offset:-4096
	global_load_dwordx4 v[20:23], v[234:235], off offset:-3072
	global_load_dwordx4 v[24:27], v[234:235], off offset:-2048
	global_load_dwordx4 v[28:31], v[234:235], off offset:-1024
	global_load_dwordx4 v[32:35], v[234:235], off
	global_load_dwordx4 v[36:39], v[234:235], off offset:1024
	global_load_dwordx4 v[40:43], v[234:235], off offset:2048
	global_load_dwordx4 v[44:47], v[234:235], off offset:3072
	v_lshl_add_u64 v[244:245], v[244:245], 0, s[8:9]
	s_add_i32 s5, s5, s82
	s_waitcnt vmcnt(48)
	v_pk_mul_f32 v[212:213], v[48:49], v[48:49]
	v_pk_fma_f32 v[212:213], v[50:51], v[50:51], v[212:213]
	v_pk_mul_f32 v[214:215], v[52:53], v[52:53]
	v_pk_fma_f32 v[214:215], v[54:55], v[54:55], v[214:215]
	v_pk_mul_f32 v[216:217], v[56:57], v[56:57]
	v_pk_fma_f32 v[216:217], v[58:59], v[58:59], v[216:217]
	v_pk_mul_f32 v[218:219], v[60:61], v[60:61]
	v_pk_fma_f32 v[218:219], v[62:63], v[62:63], v[218:219]
	v_pk_fma_f32 v[212:213], v[64:65], v[64:65], v[212:213]
	v_pk_fma_f32 v[212:213], v[66:67], v[66:67], v[212:213]
	v_pk_fma_f32 v[214:215], v[68:69], v[68:69], v[214:215]
	v_pk_fma_f32 v[214:215], v[70:71], v[70:71], v[214:215]
	v_pk_fma_f32 v[216:217], v[72:73], v[72:73], v[216:217]
	v_pk_fma_f32 v[216:217], v[74:75], v[74:75], v[216:217]
	v_pk_fma_f32 v[218:219], v[76:77], v[76:77], v[218:219]
	v_pk_fma_f32 v[218:219], v[78:79], v[78:79], v[218:219]
	v_pk_add_f32 v[212:213], v[212:213], v[214:215]
	v_pk_add_f32 v[216:217], v[216:217], v[218:219]
	v_pk_add_f32 v[212:213], v[212:213], v[216:217]
	v_add_f32_e32 v220, v212, v213
	ds_bpermute_b32 v221, v222, v220
	s_waitcnt lgkmcnt(0)
	v_add_f32_e32 v220, v220, v221
	ds_bpermute_b32 v221, v223, v220
	s_waitcnt lgkmcnt(0)
	v_add_f32_e32 v220, v220, v221
	ds_bpermute_b32 v221, v224, v220
	s_waitcnt lgkmcnt(0)
	v_add_f32_e32 v220, v220, v221
	ds_bpermute_b32 v221, v225, v220
	s_waitcnt lgkmcnt(0)
	v_add_f32_e32 v220, v220, v221
	ds_bpermute_b32 v221, v230, v220
	s_waitcnt lgkmcnt(0)
	v_add_f32_e32 v220, v220, v221
	ds_bpermute_b32 v221, v231, v220
	s_waitcnt lgkmcnt(0)
; __device__ __forceinline__ void final_norm(float* x, const float* gam, int tid) {
;     ...
; #pragma unroll
;     for (int j = 0; j < 8; ++j) xr[64 * j] = v[j] * rstd * *(const f32x4*)(gam + 4 * (lane + 64 * j));
	v_add_f32_e32 v220, v220, v221
	v_fmamk_f32 v220, v220, 0x3a000000, v228
	v_mul_f32_e32 v221, 0x4b800000, v220
	v_cmp_gt_f32_e32 vcc, s67, v220
	s_nop 1
	v_cndmask_b32_e32 v220, v220, v221, vcc
	v_rsq_f32_e32 v220, v220
	s_nop 0
	v_mul_f32_e32 v221, 0x45800000, v220
	v_cndmask_b32_e32 v220, v220, v221, vcc
	v_pk_mul_f32 v[48:49], v[48:49], v[220:221] op_sel_hi:[1,0]
	v_pk_mul_f32 v[48:49], v[180:181], v[48:49]
	v_pk_mul_f32 v[50:51], v[50:51], v[220:221] op_sel_hi:[1,0]
	v_pk_mul_f32 v[50:51], v[182:183], v[50:51]
	global_store_dwordx4 v[236:237], v[48:51], off offset:-4096
	v_pk_mul_f32 v[52:53], v[52:53], v[220:221] op_sel_hi:[1,0]
	v_pk_mul_f32 v[52:53], v[184:185], v[52:53]
	v_pk_mul_f32 v[54:55], v[54:55], v[220:221] op_sel_hi:[1,0]
	v_pk_mul_f32 v[54:55], v[186:187], v[54:55]
	global_store_dwordx4 v[236:237], v[52:55], off offset:-3072
	v_pk_mul_f32 v[56:57], v[56:57], v[220:221] op_sel_hi:[1,0]
	v_pk_mul_f32 v[56:57], v[188:189], v[56:57]
	v_pk_mul_f32 v[58:59], v[58:59], v[220:221] op_sel_hi:[1,0]
	v_pk_mul_f32 v[58:59], v[190:191], v[58:59]
	global_store_dwordx4 v[236:237], v[56:59], off offset:-2048
	v_pk_mul_f32 v[60:61], v[60:61], v[220:221] op_sel_hi:[1,0]
	v_pk_mul_f32 v[60:61], v[192:193], v[60:61]
	v_pk_mul_f32 v[62:63], v[62:63], v[220:221] op_sel_hi:[1,0]
	v_pk_mul_f32 v[62:63], v[194:195], v[62:63]
	global_store_dwordx4 v[236:237], v[60:63], off offset:-1024
	v_pk_mul_f32 v[64:65], v[64:65], v[220:221] op_sel_hi:[1,0]
	v_pk_mul_f32 v[64:65], v[196:197], v[64:65]
	v_pk_mul_f32 v[66:67], v[66:67], v[220:221] op_sel_hi:[1,0]
	v_pk_mul_f32 v[66:67], v[198:199], v[66:67]
	global_store_dwordx4 v[236:237], v[64:67], off
	v_pk_mul_f32 v[68:69], v[68:69], v[220:221] op_sel_hi:[1,0]
	v_pk_mul_f32 v[68:69], v[200:201], v[68:69]
	v_pk_mul_f32 v[70:71], v[70:71], v[220:221] op_sel_hi:[1,0]
	v_pk_mul_f32 v[70:71], v[202:203], v[70:71]
	global_store_dwordx4 v[236:237], v[68:71], off offset:1024
	v_pk_mul_f32 v[72:73], v[72:73], v[220:221] op_sel_hi:[1,0]
	v_pk_mul_f32 v[72:73], v[204:205], v[72:73]
	v_pk_mul_f32 v[74:75], v[74:75], v[220:221] op_sel_hi:[1,0]
	v_pk_mul_f32 v[74:75], v[206:207], v[74:75]
	global_store_dwordx4 v[236:237], v[72:75], off offset:2048
	v_pk_mul_f32 v[76:77], v[76:77], v[220:221] op_sel_hi:[1,0]
	v_pk_mul_f32 v[76:77], v[208:209], v[76:77]
	v_pk_mul_f32 v[78:79], v[78:79], v[220:221] op_sel_hi:[1,0]
	v_pk_mul_f32 v[78:79], v[210:211], v[78:79]
	global_store_dwordx4 v[236:237], v[76:79], off offset:3072
	s_add_i32 s4, s4, s82
	s_cmp_lt_i32 s4, 0x4000
	s_cbranch_scc0 .Lfn_done
; __device__ __forceinline__ void final_norm(float* x, const float* gam, int tid) {
;     ...
;   for (int r = gw; r < SEQ; r += nw) {
;     f32x4* xr = (f32x4*)(x + (size_t)r * DM) + lane;
;     f32x4 v[8]; float ss = 0.f;
; #pragma unroll
;     for (int j = 0; j < 8; ++j) { v[j] = xr[64 * j]; ss += v[j][0] * v[j][0] + v[j][1] * v[j][1] + v[j][2] * v[j][2] + v[j][3] * v[j][3]; }
;     const float rstd = rsqrtf(wave_sum(ss) * (1.0f / DM) + 1e-6f);
; #pragma unroll
;     for (int j = 0; j < 8; ++j) xr[64 * j] = v[j] * rstd * *(const f32x4*)(gam + 4 * (lane + 64 * j));
	s_cmp_lt_i32 s5, 0x4000
	s_cselect_b64 vcc, -1, 0
	v_cndmask_b32_e32 v236, v246, v244, vcc
	v_cndmask_b32_e32 v237, v247, v245, vcc
	global_load_dwordx4 v[48:51], v[236:237], off offset:-4096
	global_load_dwordx4 v[52:55], v[236:237], off offset:-3072
	global_load_dwordx4 v[56:59], v[236:237], off offset:-2048
	global_load_dwordx4 v[60:63], v[236:237], off offset:-1024
	global_load_dwordx4 v[64:67], v[236:237], off
	global_load_dwordx4 v[68:71], v[236:237], off offset:1024
	global_load_dwordx4 v[72:75], v[236:237], off offset:2048
	global_load_dwordx4 v[76:79], v[236:237], off offset:3072
	v_lshl_add_u64 v[244:245], v[244:245], 0, s[8:9]
	s_add_i32 s5, s5, s82
	s_waitcnt vmcnt(48)
	v_pk_mul_f32 v[212:213], v[80:81], v[80:81]
	v_pk_fma_f32 v[212:213], v[82:83], v[82:83], v[212:213]
	v_pk_mul_f32 v[214:215], v[84:85], v[84:85]
	v_pk_fma_f32 v[214:215], v[86:87], v[86:87], v[214:215]
	v_pk_mul_f32 v[216:217], v[88:89], v[88:89]
	v_pk_fma_f32 v[216:217], v[90:91], v[90:91], v[216:217]
	v_pk_mul_f32 v[218:219], v[92:93], v[92:93]
	v_pk_fma_f32 v[218:219], v[94:95], v[94:95], v[218:219]
	v_pk_fma_f32 v[212:213], v[96:97], v[96:97], v[212:213]
	v_pk_fma_f32 v[212:213], v[98:99], v[98:99], v[212:213]
	v_pk_fma_f32 v[214:215], v[100:101], v[100:101], v[214:215]
	v_pk_fma_f32 v[214:215], v[102:103], v[102:103], v[214:215]
	v_pk_fma_f32 v[216:217], v[104:105], v[104:105], v[216:217]
	v_pk_fma_f32 v[216:217], v[106:107], v[106:107], v[216:217]
	v_pk_fma_f32 v[218:219], v[108:109], v[108:109], v[218:219]
	v_pk_fma_f32 v[218:219], v[110:111], v[110:111], v[218:219]
	v_pk_add_f32 v[212:213], v[212:213], v[214:215]
	v_pk_add_f32 v[216:217], v[216:217], v[218:219]
	v_pk_add_f32 v[212:213], v[212:213], v[216:217]
	v_add_f32_e32 v220, v212, v213
	ds_bpermute_b32 v221, v222, v220
	s_waitcnt lgkmcnt(0)
	v_add_f32_e32 v220, v220, v221
	ds_bpermute_b32 v221, v223, v220
	s_waitcnt lgkmcnt(0)
	v_add_f32_e32 v220, v220, v221
	ds_bpermute_b32 v221, v224, v220
	s_waitcnt lgkmcnt(0)
	v_add_f32_e32 v220, v220, v221
	ds_bpermute_b32 v221, v225, v220
	s_waitcnt lgkmcnt(0)
	v_add_f32_e32 v220, v220, v221
	ds_bpermute_b32 v221, v230, v220
	s_waitcnt lgkmcnt(0)
	v_add_f32_e32 v220, v220, v221
	ds_bpermute_b32 v221, v231, v220
	s_waitcnt lgkmcnt(0)
	v_add_f32_e32 v220, v220, v221
	v_fmamk_f32 v220, v220, 0x3a000000, v228
	v_mul_f32_e32 v221, 0x4b800000, v220
	v_cmp_gt_f32_e32 vcc, s67, v220
	s_nop 1
	v_cndmask_b32_e32 v220, v220, v221, vcc
	v_rsq_f32_e32 v220, v220
	s_nop 0
	v_mul_f32_e32 v221, 0x45800000, v220
	v_cndmask_b32_e32 v220, v220, v221, vcc
	v_pk_mul_f32 v[80:81], v[80:81], v[220:221] op_sel_hi:[1,0]
	v_pk_mul_f32 v[80:81], v[180:181], v[80:81]
	v_pk_mul_f32 v[82:83], v[82:83], v[220:221] op_sel_hi:[1,0]
	v_pk_mul_f32 v[82:83], v[182:183], v[82:83]
	global_store_dwordx4 v[238:239], v[80:83], off offset:-4096
	v_pk_mul_f32 v[84:85], v[84:85], v[220:221] op_sel_hi:[1,0]
	v_pk_mul_f32 v[84:85], v[184:185], v[84:85]
	v_pk_mul_f32 v[86:87], v[86:87], v[220:221] op_sel_hi:[1,0]
	v_pk_mul_f32 v[86:87], v[186:187], v[86:87]
	global_store_dwordx4 v[238:239], v[84:87], off offset:-3072
	v_pk_mul_f32 v[88:89], v[88:89], v[220:221] op_sel_hi:[1,0]
	v_pk_mul_f32 v[88:89], v[188:189], v[88:89]
	v_pk_mul_f32 v[90:91], v[90:91], v[220:221] op_sel_hi:[1,0]
	v_pk_mul_f32 v[90:91], v[190:191], v[90:91]
	global_store_dwordx4 v[238:239], v[88:91], off offset:-2048
	v_pk_mul_f32 v[92:93], v[92:93], v[220:221] op_sel_hi:[1,0]
	v_pk_mul_f32 v[92:93], v[192:193], v[92:93]
	v_pk_mul_f32 v[94:95], v[94:95], v[220:221] op_sel_hi:[1,0]
	v_pk_mul_f32 v[94:95], v[194:195], v[94:95]
	global_store_dwordx4 v[238:239], v[92:95], off offset:-1024
	v_pk_mul_f32 v[96:97], v[96:97], v[220:221] op_sel_hi:[1,0]
	v_pk_mul_f32 v[96:97], v[196:197], v[96:97]
	v_pk_mul_f32 v[98:99], v[98:99], v[220:221] op_sel_hi:[1,0]
	v_pk_mul_f32 v[98:99], v[198:199], v[98:99]
	global_store_dwordx4 v[238:239], v[96:99], off
	v_pk_mul_f32 v[100:101], v[100:101], v[220:221] op_sel_hi:[1,0]
	v_pk_mul_f32 v[100:101], v[200:201], v[100:101]
	v_pk_mul_f32 v[102:103], v[102:103], v[220:221] op_sel_hi:[1,0]
	v_pk_mul_f32 v[102:103], v[202:203], v[102:103]
	global_store_dwordx4 v[238:239], v[100:103], off offset:1024
	v_pk_mul_f32 v[104:105], v[104:105], v[220:221] op_sel_hi:[1,0]
	v_pk_mul_f32 v[104:105], v[204:205], v[104:105]
	v_pk_mul_f32 v[106:107], v[106:107], v[220:221] op_sel_hi:[1,0]
	v_pk_mul_f32 v[106:107], v[206:207], v[106:107]
	global_store_dwordx4 v[238:239], v[104:107], off offset:2048
	v_pk_mul_f32 v[108:109], v[108:109], v[220:221] op_sel_hi:[1,0]
	v_pk_mul_f32 v[108:109], v[208:209], v[108:109]
	v_pk_mul_f32 v[110:111], v[110:111], v[220:221] op_sel_hi:[1,0]
	v_pk_mul_f32 v[110:111], v[210:211], v[110:111]
	global_store_dwordx4 v[238:239], v[108:111], off offset:3072
	s_add_i32 s4, s4, s82
	s_cmp_lt_i32 s4, 0x4000
	s_cbranch_scc0 .Lfn_done
	s_branch .Lfn_loop
.Lfn_done:
	s_waitcnt vmcnt(0)
.LBB0_463:
	s_or_b64 exec, exec, s[2:3]
